# prologue peW1 dot-product loop: 32 k-steps of loads per trip (64 in flight) on the 8 workgroups that own it; same accumulation order
# speedup vs baseline: 1.0065x; 1.0043x over previous
; __device__ __forceinline__ void prologue(LAS unsigned char* lds, const Ctx& P, int l) {
;     ...
;     for (int u = blockIdx.x; u < 8; u += G) { const int kv = u >> 2, cb = u & 3, col = cb * 64 + (tid & 63), ks = tid >> 6;
;         const float* pe = P.in[15 + kv] + (size_t)l * 2048; const float* w1 = P.in[17 + kv] + (size_t)l * 2048 * 256; float s = 0.f;
;         for (int k = ks * 256; k < ks * 256 + 256; ++k) s += pe[k] * w1[(size_t)k * 256 + col];
.LBB0_902:
	global_load_dword v34, v[12:13], off
	global_load_dword v114, v[10:11], off
	v_lshl_add_u64 v[10:11], v[10:11], 0, s[96:97]
	global_load_dword v35, v[12:13], off offset:4
	global_load_dword v115, v[10:11], off
	v_lshl_add_u64 v[10:11], v[10:11], 0, s[96:97]
	global_load_dword v36, v[12:13], off offset:8
	global_load_dword v116, v[10:11], off
	v_lshl_add_u64 v[10:11], v[10:11], 0, s[96:97]
	global_load_dword v37, v[12:13], off offset:12
	global_load_dword v117, v[10:11], off
	v_lshl_add_u64 v[10:11], v[10:11], 0, s[96:97]
	global_load_dword v38, v[12:13], off offset:16
	global_load_dword v118, v[10:11], off
	v_lshl_add_u64 v[10:11], v[10:11], 0, s[96:97]
	global_load_dword v39, v[12:13], off offset:20
	global_load_dword v119, v[10:11], off
	v_lshl_add_u64 v[10:11], v[10:11], 0, s[96:97]
	global_load_dword v40, v[12:13], off offset:24
	global_load_dword v120, v[10:11], off
	v_lshl_add_u64 v[10:11], v[10:11], 0, s[96:97]
	global_load_dword v41, v[12:13], off offset:28
	global_load_dword v121, v[10:11], off
	v_lshl_add_u64 v[10:11], v[10:11], 0, s[96:97]
	global_load_dword v42, v[12:13], off offset:32
	global_load_dword v122, v[10:11], off
	v_lshl_add_u64 v[10:11], v[10:11], 0, s[96:97]
	global_load_dword v43, v[12:13], off offset:36
	global_load_dword v123, v[10:11], off
	v_lshl_add_u64 v[10:11], v[10:11], 0, s[96:97]
	global_load_dword v44, v[12:13], off offset:40
	global_load_dword v124, v[10:11], off
	v_lshl_add_u64 v[10:11], v[10:11], 0, s[96:97]
	global_load_dword v45, v[12:13], off offset:44
	global_load_dword v125, v[10:11], off
	v_lshl_add_u64 v[10:11], v[10:11], 0, s[96:97]
	global_load_dword v46, v[12:13], off offset:48
	global_load_dword v126, v[10:11], off
	v_lshl_add_u64 v[10:11], v[10:11], 0, s[96:97]
	global_load_dword v47, v[12:13], off offset:52
	global_load_dword v127, v[10:11], off
	v_lshl_add_u64 v[10:11], v[10:11], 0, s[96:97]
	global_load_dword v48, v[12:13], off offset:56
	global_load_dword v128, v[10:11], off
	v_lshl_add_u64 v[10:11], v[10:11], 0, s[96:97]
	global_load_dword v49, v[12:13], off offset:60
	global_load_dword v129, v[10:11], off
	v_lshl_add_u64 v[10:11], v[10:11], 0, s[96:97]
	global_load_dword v50, v[12:13], off offset:64
	global_load_dword v130, v[10:11], off
	v_lshl_add_u64 v[10:11], v[10:11], 0, s[96:97]
	global_load_dword v51, v[12:13], off offset:68
	global_load_dword v131, v[10:11], off
	v_lshl_add_u64 v[10:11], v[10:11], 0, s[96:97]
	global_load_dword v52, v[12:13], off offset:72
	global_load_dword v132, v[10:11], off
	v_lshl_add_u64 v[10:11], v[10:11], 0, s[96:97]
	global_load_dword v53, v[12:13], off offset:76
	global_load_dword v133, v[10:11], off
	v_lshl_add_u64 v[10:11], v[10:11], 0, s[96:97]
	global_load_dword v54, v[12:13], off offset:80
	global_load_dword v134, v[10:11], off
	v_lshl_add_u64 v[10:11], v[10:11], 0, s[96:97]
	global_load_dword v55, v[12:13], off offset:84
	global_load_dword v135, v[10:11], off
	v_lshl_add_u64 v[10:11], v[10:11], 0, s[96:97]
	global_load_dword v56, v[12:13], off offset:88
	global_load_dword v136, v[10:11], off
	v_lshl_add_u64 v[10:11], v[10:11], 0, s[96:97]
	global_load_dword v57, v[12:13], off offset:92
	global_load_dword v137, v[10:11], off
	v_lshl_add_u64 v[10:11], v[10:11], 0, s[96:97]
	global_load_dword v58, v[12:13], off offset:96
	global_load_dword v138, v[10:11], off
	v_lshl_add_u64 v[10:11], v[10:11], 0, s[96:97]
	global_load_dword v59, v[12:13], off offset:100
	global_load_dword v139, v[10:11], off
	v_lshl_add_u64 v[10:11], v[10:11], 0, s[96:97]
	global_load_dword v60, v[12:13], off offset:104
	global_load_dword v140, v[10:11], off
	v_lshl_add_u64 v[10:11], v[10:11], 0, s[96:97]
	global_load_dword v61, v[12:13], off offset:108
	global_load_dword v141, v[10:11], off
	v_lshl_add_u64 v[10:11], v[10:11], 0, s[96:97]
	global_load_dword v62, v[12:13], off offset:112
	global_load_dword v142, v[10:11], off
	v_lshl_add_u64 v[10:11], v[10:11], 0, s[96:97]
	global_load_dword v63, v[12:13], off offset:116
	global_load_dword v143, v[10:11], off
	v_lshl_add_u64 v[10:11], v[10:11], 0, s[96:97]
	global_load_dword v64, v[12:13], off offset:120
	global_load_dword v144, v[10:11], off
	v_lshl_add_u64 v[10:11], v[10:11], 0, s[96:97]
	global_load_dword v65, v[12:13], off offset:124
	global_load_dword v145, v[10:11], off
	v_lshl_add_u64 v[10:11], v[10:11], 0, s[96:97]
	v_lshl_add_u64 v[12:13], v[12:13], 0, 64
	v_lshl_add_u64 v[12:13], v[12:13], 0, 64
	v_add_u32_e32 v18, 32, v18
	v_cmp_ge_i32_e64 s[0:1], v18, v16
	s_or_b64 s[6:7], s[0:1], s[6:7]
	s_waitcnt vmcnt(62)
	v_fmac_f32_e32 v0, v34, v114
	s_waitcnt vmcnt(60)
	v_fmac_f32_e32 v0, v35, v115
	s_waitcnt vmcnt(58)
	v_fmac_f32_e32 v0, v36, v116
	s_waitcnt vmcnt(56)
	v_fmac_f32_e32 v0, v37, v117
	s_waitcnt vmcnt(54)
	v_fmac_f32_e32 v0, v38, v118
	s_waitcnt vmcnt(52)
	v_fmac_f32_e32 v0, v39, v119
	s_waitcnt vmcnt(50)
	v_fmac_f32_e32 v0, v40, v120
	s_waitcnt vmcnt(48)
	v_fmac_f32_e32 v0, v41, v121
	s_waitcnt vmcnt(46)
	v_fmac_f32_e32 v0, v42, v122
	s_waitcnt vmcnt(44)
	v_fmac_f32_e32 v0, v43, v123
	s_waitcnt vmcnt(42)
	v_fmac_f32_e32 v0, v44, v124
	s_waitcnt vmcnt(40)
	v_fmac_f32_e32 v0, v45, v125
	s_waitcnt vmcnt(38)
	v_fmac_f32_e32 v0, v46, v126
	s_waitcnt vmcnt(36)
	v_fmac_f32_e32 v0, v47, v127
	s_waitcnt vmcnt(34)
	v_fmac_f32_e32 v0, v48, v128
	s_waitcnt vmcnt(32)
	v_fmac_f32_e32 v0, v49, v129
	s_waitcnt vmcnt(30)
	v_fmac_f32_e32 v0, v50, v130
	s_waitcnt vmcnt(28)
	v_fmac_f32_e32 v0, v51, v131
	s_waitcnt vmcnt(26)
	v_fmac_f32_e32 v0, v52, v132
	s_waitcnt vmcnt(24)
	v_fmac_f32_e32 v0, v53, v133
	s_waitcnt vmcnt(22)
	v_fmac_f32_e32 v0, v54, v134
	s_waitcnt vmcnt(20)
	v_fmac_f32_e32 v0, v55, v135
	s_waitcnt vmcnt(18)
	v_fmac_f32_e32 v0, v56, v136
	s_waitcnt vmcnt(16)
	v_fmac_f32_e32 v0, v57, v137
	s_waitcnt vmcnt(14)
	v_fmac_f32_e32 v0, v58, v138
	s_waitcnt vmcnt(12)
	v_fmac_f32_e32 v0, v59, v139
	s_waitcnt vmcnt(10)
	v_fmac_f32_e32 v0, v60, v140
	s_waitcnt vmcnt(8)
	v_fmac_f32_e32 v0, v61, v141
	s_waitcnt vmcnt(6)
	v_fmac_f32_e32 v0, v62, v142
	s_waitcnt vmcnt(4)
	v_fmac_f32_e32 v0, v63, v143
	s_waitcnt vmcnt(2)
	v_fmac_f32_e32 v0, v64, v144
	s_waitcnt vmcnt(0)
	v_fmac_f32_e32 v0, v65, v145
	s_andn2_b64 exec, exec, s[6:7]
	s_cbranch_execnz .LBB0_902
; __device__ __forceinline__ void prologue(LAS unsigned char* lds, const Ctx& P, int l) {
;     ...
;         tile[tid] = s; __syncthreads();
;         if (tid < 64) { float a = 0.f;
; #pragma unroll
;             for (int j = 0; j < 8; ++j) a += tile[j * 64 + tid];
;             ((float*)(ws + WS_PEW1))[kv * 256 + col] = a; }
;         __syncthreads(); }
	s_or_b64 exec, exec, s[6:7]
	ds_write_b32 v15, v0
	s_waitcnt lgkmcnt(0)
	s_barrier
	s_and_saveexec_b64 s[0:1], vcc
	s_cbranch_execz .LBB0_900
	ds_read2st64_b32 v[10:11], v15 offset1:1
	s_lshl_b32 s6, s9, 6
	s_and_b32 s6, s6, 0xc0
	v_or_b32_e32 v0, s6, v14
	s_waitcnt lgkmcnt(0)
	v_add_f32_e32 v10, 0, v10
	v_add_f32_e32 v12, v10, v11
	ds_read2st64_b32 v[10:11], v15 offset0:2 offset1:3
	s_waitcnt lgkmcnt(0)
	v_add_f32_e32 v10, v12, v10
	v_add_f32_e32 v12, v10, v11
	ds_read2st64_b32 v[10:11], v15 offset0:4 offset1:5
	s_waitcnt lgkmcnt(0)
	v_add_f32_e32 v10, v12, v10
	v_add_f32_e32 v12, v10, v11
	ds_read2st64_b32 v[10:11], v15 offset0:6 offset1:7
	s_waitcnt lgkmcnt(0)
	v_add_f32_e32 v10, v12, v10
	v_add_f32_e32 v12, v10, v11
	v_lshl_or_b32 v10, s12, 8, v0
	v_ashrrev_i32_e32 v11, 31, v10
	v_lshl_add_u64 v[10:11], v[10:11], 2, s[4:5]
	global_store_dword v[10:11], v12, off
	s_branch .LBB0_900

; __device__ __forceinline__ void prologue(LAS unsigned char* lds, const Ctx& P, int l) {
;     ...
;     for (int u = blockIdx.x; u < 8; u += G) { const int kv = u >> 2, cb = u & 3, col = cb * 64 + (tid & 63), ks = tid >> 6;
;         const float* pe = P.in[15 + kv] + (size_t)l * 2048; const float* w1 = P.in[17 + kv] + (size_t)l * 2048 * 256; float s = 0.f;
;         for (int k = ks * 256; k < ks * 256 + 256; ++k) s += pe[k] * w1[(size_t)k * 256 + col];
;         tile[tid] = s; __syncthreads();
;         if (tid < 64) { float a = 0.f;
; #pragma unroll
;             for (int j = 0; j < 8; ++j) a += tile[j * 64 + tid];
;             ((float*)(ws + WS_PEW1))[kv * 256 + col] = a; }
;         __syncthreads(); }
.LBB0_1045:
	global_load_dword v34, v[8:9], off
	global_load_dword v114, v[6:7], off
	v_lshl_add_u64 v[6:7], v[6:7], 0, s[96:97]
	global_load_dword v35, v[8:9], off offset:4
	global_load_dword v115, v[6:7], off
	v_lshl_add_u64 v[6:7], v[6:7], 0, s[96:97]
	global_load_dword v36, v[8:9], off offset:8
	global_load_dword v116, v[6:7], off
	v_lshl_add_u64 v[6:7], v[6:7], 0, s[96:97]
	global_load_dword v37, v[8:9], off offset:12
	global_load_dword v117, v[6:7], off
	v_lshl_add_u64 v[6:7], v[6:7], 0, s[96:97]
	global_load_dword v38, v[8:9], off offset:16
	global_load_dword v118, v[6:7], off
	v_lshl_add_u64 v[6:7], v[6:7], 0, s[96:97]
	global_load_dword v39, v[8:9], off offset:20
	global_load_dword v119, v[6:7], off
	v_lshl_add_u64 v[6:7], v[6:7], 0, s[96:97]
	global_load_dword v40, v[8:9], off offset:24
	global_load_dword v120, v[6:7], off
	v_lshl_add_u64 v[6:7], v[6:7], 0, s[96:97]
	global_load_dword v41, v[8:9], off offset:28
	global_load_dword v121, v[6:7], off
	v_lshl_add_u64 v[6:7], v[6:7], 0, s[96:97]
	global_load_dword v42, v[8:9], off offset:32
	global_load_dword v122, v[6:7], off
	v_lshl_add_u64 v[6:7], v[6:7], 0, s[96:97]
	global_load_dword v43, v[8:9], off offset:36
	global_load_dword v123, v[6:7], off
	v_lshl_add_u64 v[6:7], v[6:7], 0, s[96:97]
	global_load_dword v44, v[8:9], off offset:40
	global_load_dword v124, v[6:7], off
	v_lshl_add_u64 v[6:7], v[6:7], 0, s[96:97]
	global_load_dword v45, v[8:9], off offset:44
	global_load_dword v125, v[6:7], off
	v_lshl_add_u64 v[6:7], v[6:7], 0, s[96:97]
	global_load_dword v46, v[8:9], off offset:48
	global_load_dword v126, v[6:7], off
	v_lshl_add_u64 v[6:7], v[6:7], 0, s[96:97]
	global_load_dword v47, v[8:9], off offset:52
	global_load_dword v127, v[6:7], off
	v_lshl_add_u64 v[6:7], v[6:7], 0, s[96:97]
	global_load_dword v48, v[8:9], off offset:56
	global_load_dword v128, v[6:7], off
	v_lshl_add_u64 v[6:7], v[6:7], 0, s[96:97]
	global_load_dword v49, v[8:9], off offset:60
	global_load_dword v129, v[6:7], off
	v_lshl_add_u64 v[6:7], v[6:7], 0, s[96:97]
	global_load_dword v50, v[8:9], off offset:64
	global_load_dword v130, v[6:7], off
	v_lshl_add_u64 v[6:7], v[6:7], 0, s[96:97]
	global_load_dword v51, v[8:9], off offset:68
	global_load_dword v131, v[6:7], off
	v_lshl_add_u64 v[6:7], v[6:7], 0, s[96:97]
	global_load_dword v52, v[8:9], off offset:72
	global_load_dword v132, v[6:7], off
	v_lshl_add_u64 v[6:7], v[6:7], 0, s[96:97]
	global_load_dword v53, v[8:9], off offset:76
	global_load_dword v133, v[6:7], off
	v_lshl_add_u64 v[6:7], v[6:7], 0, s[96:97]
	global_load_dword v54, v[8:9], off offset:80
	global_load_dword v134, v[6:7], off
	v_lshl_add_u64 v[6:7], v[6:7], 0, s[96:97]
	global_load_dword v55, v[8:9], off offset:84
	global_load_dword v135, v[6:7], off
	v_lshl_add_u64 v[6:7], v[6:7], 0, s[96:97]
	global_load_dword v56, v[8:9], off offset:88
	global_load_dword v136, v[6:7], off
	v_lshl_add_u64 v[6:7], v[6:7], 0, s[96:97]
	global_load_dword v57, v[8:9], off offset:92
	global_load_dword v137, v[6:7], off
	v_lshl_add_u64 v[6:7], v[6:7], 0, s[96:97]
	global_load_dword v58, v[8:9], off offset:96
	global_load_dword v138, v[6:7], off
	v_lshl_add_u64 v[6:7], v[6:7], 0, s[96:97]
	global_load_dword v59, v[8:9], off offset:100
	global_load_dword v139, v[6:7], off
	v_lshl_add_u64 v[6:7], v[6:7], 0, s[96:97]
	global_load_dword v60, v[8:9], off offset:104
	global_load_dword v140, v[6:7], off
	v_lshl_add_u64 v[6:7], v[6:7], 0, s[96:97]
	global_load_dword v61, v[8:9], off offset:108
	global_load_dword v141, v[6:7], off
	v_lshl_add_u64 v[6:7], v[6:7], 0, s[96:97]
	global_load_dword v62, v[8:9], off offset:112
	global_load_dword v142, v[6:7], off
	v_lshl_add_u64 v[6:7], v[6:7], 0, s[96:97]
	global_load_dword v63, v[8:9], off offset:116
	global_load_dword v143, v[6:7], off
	v_lshl_add_u64 v[6:7], v[6:7], 0, s[96:97]
	global_load_dword v64, v[8:9], off offset:120
	global_load_dword v144, v[6:7], off
	v_lshl_add_u64 v[6:7], v[6:7], 0, s[96:97]
	global_load_dword v65, v[8:9], off offset:124
	global_load_dword v145, v[6:7], off
	v_lshl_add_u64 v[6:7], v[6:7], 0, s[96:97]
	v_lshl_add_u64 v[8:9], v[8:9], 0, 64
	v_lshl_add_u64 v[8:9], v[8:9], 0, 64
	v_add_u32_e32 v14, 32, v14
	v_cmp_ge_i32_e64 s[0:1], v14, v12
	s_or_b64 s[8:9], s[0:1], s[8:9]
	s_waitcnt vmcnt(62)
	v_fmac_f32_e32 v0, v34, v114
	s_waitcnt vmcnt(60)
	v_fmac_f32_e32 v0, v35, v115
	s_waitcnt vmcnt(58)
	v_fmac_f32_e32 v0, v36, v116
	s_waitcnt vmcnt(56)
	v_fmac_f32_e32 v0, v37, v117
	s_waitcnt vmcnt(54)
	v_fmac_f32_e32 v0, v38, v118
	s_waitcnt vmcnt(52)
	v_fmac_f32_e32 v0, v39, v119
	s_waitcnt vmcnt(50)
	v_fmac_f32_e32 v0, v40, v120
	s_waitcnt vmcnt(48)
	v_fmac_f32_e32 v0, v41, v121
	s_waitcnt vmcnt(46)
	v_fmac_f32_e32 v0, v42, v122
	s_waitcnt vmcnt(44)
	v_fmac_f32_e32 v0, v43, v123
	s_waitcnt vmcnt(42)
	v_fmac_f32_e32 v0, v44, v124
	s_waitcnt vmcnt(40)
	v_fmac_f32_e32 v0, v45, v125
	s_waitcnt vmcnt(38)
	v_fmac_f32_e32 v0, v46, v126
	s_waitcnt vmcnt(36)
	v_fmac_f32_e32 v0, v47, v127
	s_waitcnt vmcnt(34)
	v_fmac_f32_e32 v0, v48, v128
	s_waitcnt vmcnt(32)
	v_fmac_f32_e32 v0, v49, v129
	s_waitcnt vmcnt(30)
	v_fmac_f32_e32 v0, v50, v130
	s_waitcnt vmcnt(28)
	v_fmac_f32_e32 v0, v51, v131
	s_waitcnt vmcnt(26)
	v_fmac_f32_e32 v0, v52, v132
	s_waitcnt vmcnt(24)
	v_fmac_f32_e32 v0, v53, v133
	s_waitcnt vmcnt(22)
	v_fmac_f32_e32 v0, v54, v134
	s_waitcnt vmcnt(20)
	v_fmac_f32_e32 v0, v55, v135
	s_waitcnt vmcnt(18)
	v_fmac_f32_e32 v0, v56, v136
	s_waitcnt vmcnt(16)
	v_fmac_f32_e32 v0, v57, v137
	s_waitcnt vmcnt(14)
	v_fmac_f32_e32 v0, v58, v138
	s_waitcnt vmcnt(12)
	v_fmac_f32_e32 v0, v59, v139
	s_waitcnt vmcnt(10)
	v_fmac_f32_e32 v0, v60, v140
	s_waitcnt vmcnt(8)
	v_fmac_f32_e32 v0, v61, v141
	s_waitcnt vmcnt(6)
	v_fmac_f32_e32 v0, v62, v142
	s_waitcnt vmcnt(4)
	v_fmac_f32_e32 v0, v63, v143
	s_waitcnt vmcnt(2)
	v_fmac_f32_e32 v0, v64, v144
	s_waitcnt vmcnt(0)
	v_fmac_f32_e32 v0, v65, v145
	s_andn2_b64 exec, exec, s[8:9]
	s_cbranch_execnz .LBB0_1045
	s_or_b64 exec, exec, s[8:9]
	ds_write_b32 v11, v0
	s_waitcnt lgkmcnt(0)
	s_barrier
	s_and_saveexec_b64 s[0:1], vcc
	s_cbranch_execz .LBB0_1043
	ds_read2st64_b32 v[6:7], v11 offset1:1
	ds_read2st64_b32 v[8:9], v11 offset0:2 offset1:3
	ds_read2st64_b32 v[14:15], v11 offset0:4 offset1:5
	ds_read2st64_b32 v[16:17], v11 offset0:6 offset1:7
	s_lshl_b32 s8, s11, 6
	s_and_b32 s8, s8, 0xc0
	v_or_b32_e32 v0, s8, v10
	s_waitcnt lgkmcnt(3)
	v_add_f32_e32 v6, 0, v6
	v_add_f32_e32 v6, v6, v7
	s_waitcnt lgkmcnt(2)
	v_add_f32_e32 v6, v6, v8
	v_add_f32_e32 v6, v6, v9
	s_waitcnt lgkmcnt(1)
	v_add_f32_e32 v6, v6, v14
	v_add_f32_e32 v6, v6, v15
	s_waitcnt lgkmcnt(0)
	v_add_f32_e32 v6, v6, v16
	v_add_f32_e32 v8, v6, v17
	v_lshl_or_b32 v6, s12, 8, v0
	v_ashrrev_i32_e32 v7, 31, v6
	v_lshl_add_u64 v[6:7], v[6:7], 2, s[4:5]
	global_store_dword v[6:7], v8, off
	s_branch .LBB0_1043
